# v84 with the sample-first half of the memory-attention workgroups chosen per (batch, head) group (workgroup id bit 7) instead of bit 3, so the 16 units sharing a K/V block run at the same time on thei
# speedup vs baseline: 1.0084x; 1.0004x over previous
; #define LAS __attribute__((address_space(3)))
; template <bool SAMPLE>
; __device__ __forceinline__ void mem_unit(const Params& p, int l, LAS unsigned char* lds, int unit, int tid, int wave, int lane) {
;     const bf16* MQ = (const bf16*)(p.ws + W_MQ); bf16* MO = (bf16*)(p.ws + W_MO);
;     LAS bf16* Kl = (LAS bf16*)lds; LAS bf16* Vt = (LAS bf16*)(lds + MEM_VOFF);
;     int b, h, qt;
;     if (!SAMPLE) { qt = unit & 15; h = (unit >> 4) & 3; b = unit >> 6; } else { h = unit & 3; b = unit >> 2; qt = 0; }
;     {
;         const int sub = tid & 15;
;         float kg[8]; pg8::ld8f(p.in[I_MKG] + l * 128 + 8 * sub, kg);
; __global__ void __launch_bounds__(NTHR, 2) fwd_megakernel(Params p) {
;     ...
;         { PHASE_IDS
;         for (int rep = 0; rep < REP_LIGHT * REP_MEM; ++rep)
;         for (int u = bx; u < 256 + 512; u += G) { if (u < 256) mem_unit<false>(p, l, lds, u, tid, wave, lane); else mem_unit<true>(p, l, lds, u - 256, tid, wave, lane); } }
.LBB0_594:
	s_or_b64 exec, exec, s[0:1]
	v_readlane_b32 s0, v240, 14
	s_waitcnt lgkmcnt(0)
	v_mov_b32_e32 v0, v216
	v_readlane_b32 s1, v240, 15
	s_barrier
	s_and_b64 vcc, exec, s[0:1]
	v_readfirstlane_b32 s0, v0
	s_cbranch_vccnz .LBB0_633
	s_cmp_lt_u32 s0, 64
	s_cselect_b64 s[4:5], -1, 0
	s_ashr_i32 s0, s0, 2
	s_and_b32 s6, s0, -16
	s_ashr_i32 s7, s6, 31
	s_add_u32 s28, s94, 0x1a300000
	s_addc_u32 s29, s95, 0
	v_lshlrev_b32_e32 v1, 3, v0
	s_add_u32 s12, s92, 0xaade000
	v_and_b32_e32 v80, 0x78, v1
	v_readlane_b32 s0, v239, 14
	s_addc_u32 s13, s93, 0
	v_ashrrev_i32_e32 v81, 4, v0
	v_and_b32_e32 v94, 15, v0
	v_bfe_u32 v95, v0, 4, 2
	v_mov_b32_e32 v83, 0
	v_lshlrev_b32_e32 v82, 2, v80
	v_readlane_b32 s1, v239, 15
	v_lshlrev_b32_e32 v0, 1, v80
	s_add_u32 s14, s92, 0xaede000
	v_lshl_add_u64 v[84:85], s[0:1], 0, v[82:83]
	s_mov_b32 s11, 0
	v_add_u32_e32 v96, 0, v0
	v_add_u32_e32 v97, s90, v0
	v_lshl_add_u64 v[86:87], s[48:49], 0, v[82:83]
	s_addc_u32 s15, s93, 0
	s_movk_i32 s30, 0x110
	v_mov_b32_e32 v98, 0x358637bd
	s_mov_b32 s31, 0x800000
	s_mov_b32 s33, 0xff800000
	v_mbcnt_hi_u32_b32 v99, -1, v217
	s_mov_b32 s34, s63
	s_mov_b32 s35, s63
	v_readlane_b32 s98, v240, 1
	s_cmpk_eq_u32 s98, 0x100
	s_cselect_b32 s99, 1, 0
	s_lshr_b32 s98, s63, 7
	s_and_b32 s99, s99, s98
	s_and_b32 s99, s99, 1
	s_lshl_b32 s98, s99, 8
	s_add_i32 s35, s35, s98
	s_mov_b32 s34, s35
	s_mul_i32 s99, s99, 0x300
	s_cmp_lg_u32 s99, 0
	s_cselect_b32 s98, s35, -1
	s_nop 0
	s_nop 0
	s_nop 0
	s_nop 0
	s_nop 0
	s_nop 0
	s_nop 0
	s_nop 0
	s_nop 0
	s_nop 0
	s_nop 0
	s_nop 0
	s_nop 0
	s_branch .LBB0_597

; #define LAS __attribute__((address_space(3)))
; template <bool SAMPLE>
; __device__ __forceinline__ void mem_unit(const Params& p, int l, LAS unsigned char* lds, int unit, int tid, int wave, int lane) {
;     const bf16* MQ = (const bf16*)(p.ws + W_MQ); bf16* MO = (bf16*)(p.ws + W_MO);
;     LAS bf16* Kl = (LAS bf16*)lds; LAS bf16* Vt = (LAS bf16*)(lds + MEM_VOFF);
;     int b, h, qt;
;     if (!SAMPLE) { qt = unit & 15; h = (unit >> 4) & 3; b = unit >> 6; } else { h = unit & 3; b = unit >> 2; qt = 0; }
;     {
;         const int sub = tid & 15;
;         float kg[8]; pg8::ld8f(p.in[I_MKG] + l * 128 + 8 * sub, kg);
; __global__ void __launch_bounds__(NTHR, 2) fwd_megakernel(Params p) {
;     ...
;         { PHASE_IDS
;         for (int rep = 0; rep < REP_LIGHT * REP_MEM; ++rep)
;         for (int u = bx; u < 256 + 512; u += G) { if (u < 256) mem_unit<false>(p, l, lds, u, tid, wave, lane); else mem_unit<true>(p, l, lds, u - 256, tid, wave, lane); } }
.LBB0_2725:
	s_or_b64 exec, exec, s[0:1]
	v_readlane_b32 s0, v240, 14
	s_waitcnt lgkmcnt(0)
	v_mov_b32_e32 v0, v216
	v_readlane_b32 s1, v240, 15
	s_barrier
	s_and_b64 vcc, exec, s[0:1]
	v_readfirstlane_b32 s0, v0
	s_cbranch_vccnz .LBB0_2764
	s_cmp_lt_u32 s0, 64
	s_cselect_b64 s[6:7], -1, 0
	s_ashr_i32 s0, s0, 2
	s_and_b32 s4, s0, -16
	s_ashr_i32 s5, s4, 31
	v_lshlrev_b32_e32 v1, 3, v0
	s_add_u32 s12, s92, 0xaade000
	v_and_b32_e32 v80, 0x78, v1
	v_readlane_b32 s0, v239, 14
	s_addc_u32 s13, s93, 0
	v_ashrrev_i32_e32 v81, 4, v0
	s_waitcnt vmcnt(0)
	v_and_b32_e32 v94, 15, v0
	v_bfe_u32 v95, v0, 4, 2
	v_mov_b32_e32 v83, 0
	v_lshlrev_b32_e32 v82, 2, v80
	v_readlane_b32 s1, v239, 15
	v_lshlrev_b32_e32 v0, 1, v80
	s_add_u32 s14, s92, 0xaede000
	v_lshl_add_u64 v[84:85], s[0:1], 0, v[82:83]
	s_mov_b32 s11, 0
	v_add_u32_e32 v96, 0, v0
	v_add_u32_e32 v97, s90, v0
	v_lshl_add_u64 v[86:87], s[48:49], 0, v[82:83]
	s_addc_u32 s15, s93, 0
	s_movk_i32 s22, 0x110
	v_mov_b32_e32 v98, 0x358637bd
	s_mov_b32 s23, 0x800000
	s_mov_b32 s24, 0xff800000
	v_mbcnt_hi_u32_b32 v99, -1, v217
	s_mov_b32 s25, s63
	s_mov_b32 s26, s63
	v_readlane_b32 s98, v240, 1
	s_cmpk_eq_u32 s98, 0x100
	s_cselect_b32 s99, 1, 0
	s_lshr_b32 s98, s63, 7
	s_and_b32 s99, s99, s98
	s_and_b32 s99, s99, 1
	s_lshl_b32 s98, s99, 8
	s_add_i32 s26, s26, s98
	s_mov_b32 s25, s26
	s_mul_i32 s99, s99, 0x300
	s_cmp_lg_u32 s99, 0
	s_cselect_b32 s98, s26, -1
	s_nop 0
	s_nop 0
	s_nop 0
	s_nop 0
	s_nop 0
	s_nop 0
	s_nop 0
	s_nop 0
	s_nop 0
	s_nop 0
	s_nop 0
	s_nop 0
	s_nop 0
	s_branch .LBB0_2728
